# P2 token jobs touch the next row of the wave right after issuing their own loads (cache prefetch), counted waits adjusted
# baseline (speedup 1.0000x reference)
.LBB0_189:
	v_mov_b64_e32 v[0:1], s[12:13]
	v_mad_i64_i32 v[118:119], s[8:9], v116, s49, v[0:1]
	v_lshlrev_b32_e32 v120, 1, v88
	v_mov_b32_e32 v121, v91
	v_lshl_add_u64 v[122:123], v[118:119], 0, v[120:121]
	global_load_dwordx4 v[0:3], v[122:123], off
	global_load_dwordx4 v[80:83], v[104:105], off
	global_load_dwordx4 v[76:79], v[104:105], off offset:16
	v_and_b32_e32 v90, 63, v116
	global_load_dwordx4 v[84:87], v[122:123], off offset:1024
	global_load_dwordx4 v[72:75], v[122:123], off offset:2048
	v_ashrrev_i32_e32 v117, 31, v116
	v_cmp_lt_i32_e64 s[8:9], 0, v89
	s_waitcnt vmcnt(4)
	v_lshlrev_b32_e32 v128, 16, v0
	v_and_b32_e32 v129, 0xffff0000, v0
	v_and_b32_e32 v134, 0xffff0000, v1
	v_lshlrev_b32_e32 v135, 16, v1
	v_pk_mul_f32 v[0:1], v[128:129], v[128:129]
	v_and_b32_e32 v130, 0xffff0000, v2
	v_lshlrev_b32_e32 v131, 16, v2
	v_and_b32_e32 v126, 0xffff0000, v3
	v_lshlrev_b32_e32 v127, 16, v3
	v_pk_mul_f32 v[2:3], v[134:135], v[134:135]
	v_add_f32_e32 v0, v0, v1
	v_add_f32_e32 v0, v3, v0
	v_pk_mul_f32 v[4:5], v[130:131], v[130:131]
	v_add_f32_e32 v0, v2, v0
	v_add_f32_e32 v0, v5, v0
	v_pk_mul_f32 v[6:7], v[126:127], v[126:127]
	v_add_f32_e32 v0, v4, v0
	v_add_f32_e32 v0, v7, v0
	v_add_f32_e32 v0, v6, v0
	v_and_b32_e32 v4, 0x7ff, v116
	s_nop 0
	v_add_f32_dpp v0, v0, v0 quad_perm:[1,0,3,2] row_mask:0xf bank_mask:0xf bound_ctrl:1
	s_nop 1
	v_add_f32_dpp v0, v0, v0 quad_perm:[2,3,0,1] row_mask:0xf bank_mask:0xf bound_ctrl:1
	s_nop 1
	v_mov_b32_dpp v1, v0 row_half_mirror row_mask:0xf bank_mask:0xf bound_ctrl:1
	s_nop 1
	v_add_f32_dpp v0, v1, v0 quad_perm:[3,2,1,0] row_mask:0xf bank_mask:0xf bound_ctrl:1
	v_fmamk_f32 v0, v0, 0x3c800000, v140
	v_mul_f32_e32 v1, 0x4b800000, v0
	v_cmp_gt_f32_e32 vcc, s47, v0
	s_nop 1
	v_cndmask_b32_e32 v0, v0, v1, vcc
	v_rsq_f32_e32 v0, v0
	s_nop 0
	v_mul_f32_e32 v1, 0x45800000, v0
	v_cndmask_b32_e32 v121, v0, v1, vcc
	v_mul_f32_e32 v0, v121, v128
	s_waitcnt vmcnt(3)
	v_mul_f32_e32 v124, v80, v0
	v_add_co_u32_e32 v0, vcc, 0x1000, v122
	s_nop 0
	v_mov_b32_dpp v125, v124 quad_perm:[1,0,3,2] row_mask:0xf bank_mask:0xf bound_ctrl:1
	v_addc_co_u32_e32 v1, vcc, 0, v123, vcc
	v_add_co_u32_e32 v2, vcc, 0x2000, v122
	global_load_dwordx4 v[68:71], v[122:123], off offset:3072
	global_load_dwordx4 v[40:43], v[0:1], off
	global_load_dwordx4 v[36:39], v[0:1], off offset:1024
	global_load_dwordx4 v[32:35], v[0:1], off offset:2048
	v_addc_co_u32_e32 v3, vcc, 0, v123, vcc
	global_load_dwordx4 v[28:31], v[0:1], off offset:3072
	global_load_dwordx4 v[8:11], v[2:3], off
	v_or_b32_e32 v0, 0x400, v90
	v_cmp_lt_i32_e32 vcc, s51, v116
	s_nop 1
	v_cndmask_b32_e32 v0, v4, v0, vcc
	v_lshlrev_b32_e32 v0, 6, v0
	global_load_dwordx4 v[44:47], v0, s[14:15] offset:48
	global_load_dwordx4 v[52:55], v0, s[14:15] offset:32
	global_load_dwordx4 v[56:59], v0, s[14:15] offset:16
	global_load_dwordx4 v[64:67], v0, s[14:15]
	global_load_dwordx4 v[48:51], v[106:107], off offset:16
	global_load_dwordx4 v[60:63], v[106:107], off
	global_load_dwordx4 v[12:15], v[108:109], off offset:16
	global_load_dwordx4 v[20:23], v[108:109], off
	global_load_dwordx4 v[16:19], v[110:111], off offset:16
	global_load_dwordx4 v[24:27], v[110:111], off
	global_load_dwordx4 v[0:3], v[112:113], off offset:16
	global_load_dwordx4 v[4:7], v[112:113], off
	s_add_i32 s30, s64, s3
	s_cmpk_lt_i32 s30, 0x880
	s_cselect_b32 s22, 0x2a00000, 0
	s_mov_b32 s23, 0
	s_mov_b64 s[30:31], 0x1000
	s_mov_b64 s[32:33], 0x2000
	v_lshl_add_u64 v[192:193], v[122:123], 0, s[22:23]
	v_lshl_add_u64 v[194:195], v[192:193], 0, s[30:31]
	v_lshl_add_u64 v[200:201], v[192:193], 0, s[32:33]
	global_load_dwordx4 v[196:199], v[192:193], off
	global_load_dwordx4 v[196:199], v[192:193], off offset:1024
	global_load_dwordx4 v[196:199], v[192:193], off offset:2048
	global_load_dwordx4 v[196:199], v[192:193], off offset:3072
	global_load_dwordx4 v[196:199], v[194:195], off
	global_load_dwordx4 v[196:199], v[194:195], off offset:1024
	global_load_dwordx4 v[196:199], v[194:195], off offset:2048
	global_load_dwordx4 v[196:199], v[194:195], off offset:3072
	global_load_dwordx4 v[196:199], v[200:201], off
	s_and_saveexec_b64 s[10:11], s[8:9]
	s_xor_b64 s[10:11], exec, s[10:11]
	s_cbranch_execz .LBB0_193
	v_cmp_eq_u32_e64 s[8:9], 1, v89
	s_and_saveexec_b64 s[54:55], s[8:9]
	s_cbranch_execz .LBB0_192
	s_waitcnt vmcnt(17)
	v_pk_mul_f32 v[124:125], v[64:65], v[124:125]
	s_nop 0
	v_add_f32_e32 v124, v125, v124

.LBB0_193:
	s_andn2_saveexec_b64 s[8:9], s[10:11]
	s_cbranch_execz .LBB0_195
	s_waitcnt vmcnt(17)
	v_pk_mul_f32 v[124:125], v[64:65], v[124:125]
	s_nop 0
	v_sub_f32_e32 v124, v124, v125
.LBB0_195:
	s_or_b64 exec, exec, s[8:9]
	v_mul_f32_e32 v125, v121, v129
	v_mul_f32_e32 v128, v81, v125
	v_cmp_lt_i32_e64 s[8:9], 0, v89
	s_nop 0
	v_mov_b32_dpp v129, v128 quad_perm:[1,0,3,2] row_mask:0xf bank_mask:0xf bound_ctrl:1
	s_and_saveexec_b64 s[10:11], s[8:9]
	s_xor_b64 s[10:11], exec, s[10:11]
	s_cbranch_execz .LBB0_199
	v_cmp_eq_u32_e64 s[8:9], 1, v89
	s_and_saveexec_b64 s[54:55], s[8:9]
	s_cbranch_execz .LBB0_198
	s_waitcnt vmcnt(17)
	v_pk_mul_f32 v[128:129], v[66:67], v[128:129]
	s_nop 0
	v_add_f32_e32 v128, v128, v129

.LBB0_199:
	s_andn2_saveexec_b64 s[8:9], s[10:11]
	s_cbranch_execz .LBB0_201
	s_waitcnt vmcnt(17)
	v_pk_mul_f32 v[128:129], v[66:67], v[128:129]
	s_nop 0
	v_sub_f32_e32 v128, v128, v129
.LBB0_201:
	s_or_b64 exec, exec, s[8:9]
	v_mul_f32_e32 v125, v121, v135
	v_mul_f32_e32 v132, v82, v125
	v_cmp_lt_i32_e64 s[8:9], 0, v89
	s_nop 0
	v_mov_b32_dpp v133, v132 quad_perm:[1,0,3,2] row_mask:0xf bank_mask:0xf bound_ctrl:1
	s_and_saveexec_b64 s[10:11], s[8:9]
	s_xor_b64 s[10:11], exec, s[10:11]
	s_cbranch_execz .LBB0_205
	v_cmp_eq_u32_e64 s[8:9], 1, v89
	s_and_saveexec_b64 s[54:55], s[8:9]
	s_cbranch_execz .LBB0_204
	s_waitcnt vmcnt(18)
	v_pk_mul_f32 v[132:133], v[56:57], v[132:133]
	s_nop 0
	v_add_f32_e32 v132, v132, v133

.LBB0_205:
	s_andn2_saveexec_b64 s[8:9], s[10:11]
	s_cbranch_execz .LBB0_207
	s_waitcnt vmcnt(18)
	v_pk_mul_f32 v[132:133], v[56:57], v[132:133]
	s_nop 0
	v_sub_f32_e32 v132, v132, v133
.LBB0_207:
	s_or_b64 exec, exec, s[8:9]
	v_mul_f32_e32 v125, v121, v134
	v_mul_f32_e32 v134, v83, v125
	v_cmp_lt_i32_e64 s[8:9], 0, v89
	s_nop 0
	v_mov_b32_dpp v135, v134 quad_perm:[1,0,3,2] row_mask:0xf bank_mask:0xf bound_ctrl:1
	s_and_saveexec_b64 s[10:11], s[8:9]
	s_xor_b64 s[10:11], exec, s[10:11]
	s_cbranch_execz .LBB0_211
	v_cmp_eq_u32_e64 s[8:9], 1, v89
	s_and_saveexec_b64 s[54:55], s[8:9]
	s_cbranch_execz .LBB0_210
	s_waitcnt vmcnt(18)
	v_pk_mul_f32 v[134:135], v[58:59], v[134:135]
	s_nop 0
	v_add_f32_e32 v134, v134, v135

.LBB0_211:
	s_andn2_saveexec_b64 s[8:9], s[10:11]
	s_cbranch_execz .LBB0_213
	s_waitcnt vmcnt(18)
	v_pk_mul_f32 v[134:135], v[58:59], v[134:135]
	s_nop 0
	v_sub_f32_e32 v134, v134, v135
.LBB0_213:
	s_or_b64 exec, exec, s[8:9]
	v_mul_f32_e32 v125, v121, v131
	s_waitcnt vmcnt(29)
	v_mul_f32_e32 v136, v76, v125
	v_cmp_lt_i32_e64 s[8:9], 0, v89
	s_nop 0
	v_mov_b32_dpp v137, v136 quad_perm:[1,0,3,2] row_mask:0xf bank_mask:0xf bound_ctrl:1
	s_and_saveexec_b64 s[10:11], s[8:9]
	s_xor_b64 s[10:11], exec, s[10:11]
	s_cbranch_execz .LBB0_217
	v_cmp_eq_u32_e64 s[8:9], 1, v89
	s_and_saveexec_b64 s[54:55], s[8:9]
	s_cbranch_execz .LBB0_216
	s_waitcnt vmcnt(19)
	v_pk_mul_f32 v[136:137], v[52:53], v[136:137]
	s_nop 0
	v_add_f32_e32 v136, v136, v137

.LBB0_217:
	s_andn2_saveexec_b64 s[8:9], s[10:11]
	s_cbranch_execz .LBB0_219
	s_waitcnt vmcnt(19)
	v_pk_mul_f32 v[136:137], v[52:53], v[136:137]
	s_nop 0
	v_sub_f32_e32 v136, v136, v137
.LBB0_219:
	s_or_b64 exec, exec, s[8:9]
	v_mul_f32_e32 v125, v121, v130
	v_mul_f32_e32 v130, v77, v125
	v_cmp_lt_i32_e64 s[8:9], 0, v89
	s_nop 0
	v_mov_b32_dpp v131, v130 quad_perm:[1,0,3,2] row_mask:0xf bank_mask:0xf bound_ctrl:1
	s_and_saveexec_b64 s[10:11], s[8:9]
	s_xor_b64 s[10:11], exec, s[10:11]
	s_cbranch_execz .LBB0_223
	v_cmp_eq_u32_e64 s[8:9], 1, v89
	s_and_saveexec_b64 s[54:55], s[8:9]
	s_cbranch_execz .LBB0_222
	s_waitcnt vmcnt(19)
	v_pk_mul_f32 v[130:131], v[54:55], v[130:131]
	s_nop 0
	v_add_f32_e32 v130, v130, v131

.LBB0_223:
	s_andn2_saveexec_b64 s[8:9], s[10:11]
	s_cbranch_execz .LBB0_225
	s_waitcnt vmcnt(19)
	v_pk_mul_f32 v[130:131], v[54:55], v[130:131]
	s_nop 0
	v_sub_f32_e32 v130, v130, v131
.LBB0_225:
	s_or_b64 exec, exec, s[8:9]
	v_mul_f32_e32 v125, v121, v127
	v_mul_f32_e32 v138, v78, v125
	v_cmp_lt_i32_e64 s[8:9], 0, v89
	s_nop 0
	v_mov_b32_dpp v139, v138 quad_perm:[1,0,3,2] row_mask:0xf bank_mask:0xf bound_ctrl:1
	s_and_saveexec_b64 s[10:11], s[8:9]
	s_xor_b64 s[10:11], exec, s[10:11]
	s_cbranch_execz .LBB0_229
	v_cmp_eq_u32_e64 s[8:9], 1, v89
	s_and_saveexec_b64 s[54:55], s[8:9]
	s_cbranch_execz .LBB0_228
	s_waitcnt vmcnt(20)
	v_pk_mul_f32 v[138:139], v[44:45], v[138:139]
	s_nop 0
	v_add_f32_e32 v138, v138, v139

.LBB0_229:
	s_andn2_saveexec_b64 s[8:9], s[10:11]
	s_cbranch_execz .LBB0_231
	s_waitcnt vmcnt(20)
	v_pk_mul_f32 v[138:139], v[44:45], v[138:139]
	s_nop 0
	v_sub_f32_e32 v138, v138, v139
.LBB0_231:
	s_or_b64 exec, exec, s[8:9]
	v_mul_f32_e32 v121, v121, v126
	v_mul_f32_e32 v126, v79, v121
	v_cmp_lt_i32_e64 s[8:9], 0, v89
	s_nop 0
	v_mov_b32_dpp v127, v126 quad_perm:[1,0,3,2] row_mask:0xf bank_mask:0xf bound_ctrl:1
	s_and_saveexec_b64 s[10:11], s[8:9]
	s_xor_b64 s[10:11], exec, s[10:11]
	s_cbranch_execz .LBB0_235
	v_cmp_eq_u32_e64 s[8:9], 1, v89
	s_and_saveexec_b64 s[54:55], s[8:9]
	s_cbranch_execz .LBB0_234
	s_waitcnt vmcnt(20)
	v_pk_mul_f32 v[126:127], v[46:47], v[126:127]
	s_nop 0
	v_add_f32_e32 v126, v126, v127

.LBB0_235:
	s_andn2_saveexec_b64 s[8:9], s[10:11]
	s_cbranch_execz .LBB0_237
	s_waitcnt vmcnt(20)
	v_pk_mul_f32 v[126:127], v[46:47], v[126:127]
	s_nop 0
	v_sub_f32_e32 v126, v126, v127
.LBB0_237:
	s_or_b64 exec, exec, s[8:9]
	v_mul_f32_e32 v125, 0x3e38aa3b, v134
	v_mul_f32_e32 v127, 0x3e38aa3b, v132
	v_mul_f32_e32 v128, 0x3e38aa3b, v128
	v_mul_f32_e32 v124, 0x3e38aa3b, v124
	v_mul_f32_e32 v121, 0x3e38aa3b, v138
	v_mul_f32_e32 v138, 0x3e38aa3b, v130
	v_cvt_pk_bf16_f32 v130, v124, v128
	v_cvt_pk_bf16_f32 v131, v127, v125
	s_waitcnt vmcnt(28)
	v_lshlrev_b32_e32 v124, 16, v84
	v_and_b32_e32 v125, 0xffff0000, v84
	v_pk_mul_f32 v[132:133], v[124:125], v[124:125]
	v_and_b32_e32 v128, 0xffff0000, v85
	v_lshlrev_b32_e32 v129, 16, v85
	v_pk_mul_f32 v[84:85], v[128:129], v[128:129]
	v_add_f32_e32 v132, v132, v133
	v_mul_f32_e32 v141, 0x3e38aa3b, v126
	v_and_b32_e32 v126, 0xffff0000, v86
	v_lshlrev_b32_e32 v127, 16, v86
	v_add_f32_e32 v85, v85, v132
	v_pk_mul_f32 v[134:135], v[126:127], v[126:127]
	v_add_f32_e32 v84, v84, v85
	v_and_b32_e32 v86, 0xffff0000, v87
	v_lshlrev_b32_e32 v87, 16, v87
	v_add_f32_e32 v84, v135, v84
	v_mul_f32_e32 v139, 0x3e38aa3b, v136
	v_pk_mul_f32 v[136:137], v[86:87], v[86:87]
	v_add_f32_e32 v84, v134, v84
	v_add_f32_e32 v84, v137, v84
	v_add_f32_e32 v84, v136, v84
	v_cvt_pk_bf16_f32 v133, v121, v141
	v_cvt_pk_bf16_f32 v132, v139, v138
	v_add_f32_dpp v84, v84, v84 quad_perm:[1,0,3,2] row_mask:0xf bank_mask:0xf bound_ctrl:1
	global_store_dwordx4 v[122:123], v[130:133], off
	s_nop 0
	v_add_f32_dpp v84, v84, v84 quad_perm:[2,3,0,1] row_mask:0xf bank_mask:0xf bound_ctrl:1
	s_nop 1
	v_mov_b32_dpp v85, v84 row_half_mirror row_mask:0xf bank_mask:0xf bound_ctrl:1
	s_nop 1
	v_add_f32_dpp v84, v85, v84 quad_perm:[3,2,1,0] row_mask:0xf bank_mask:0xf bound_ctrl:1
	v_fmamk_f32 v84, v84, 0x3c800000, v140
	v_mul_f32_e32 v85, 0x4b800000, v84
	v_cmp_gt_f32_e64 s[8:9], s47, v84
	s_nop 1
	v_cndmask_b32_e64 v84, v84, v85, s[8:9]
	v_rsq_f32_e32 v84, v84
	s_nop 0
	v_mul_f32_e32 v85, 0x45800000, v84
	v_cndmask_b32_e64 v121, v84, v85, s[8:9]
	v_mul_f32_e32 v84, v121, v124
	v_mul_f32_e32 v84, v80, v84
	v_cmp_lt_i32_e64 s[8:9], 0, v89
	s_nop 0
	v_mov_b32_dpp v85, v84 quad_perm:[1,0,3,2] row_mask:0xf bank_mask:0xf bound_ctrl:1
	s_and_saveexec_b64 s[10:11], s[8:9]
	s_xor_b64 s[10:11], exec, s[10:11]
	s_cbranch_execz .LBB0_241
	v_cmp_eq_u32_e64 s[8:9], 1, v89
	s_and_saveexec_b64 s[54:55], s[8:9]
	s_cbranch_execz .LBB0_240
	s_waitcnt vmcnt(18)
	v_pk_mul_f32 v[84:85], v[64:65], v[84:85]
	s_nop 0
	v_add_f32_e32 v84, v85, v84

.LBB0_241:
	s_andn2_saveexec_b64 s[8:9], s[10:11]
	s_cbranch_execz .LBB0_243
	s_waitcnt vmcnt(18)
	v_pk_mul_f32 v[84:85], v[64:65], v[84:85]
	s_nop 0
	v_sub_f32_e32 v84, v84, v85
.LBB0_243:
	s_or_b64 exec, exec, s[8:9]
	v_mul_f32_e32 v80, v121, v125
	v_mul_f32_e32 v80, v81, v80
	v_cmp_lt_i32_e64 s[8:9], 0, v89
	s_nop 0
	v_mov_b32_dpp v81, v80 quad_perm:[1,0,3,2] row_mask:0xf bank_mask:0xf bound_ctrl:1
	s_and_saveexec_b64 s[10:11], s[8:9]
	s_xor_b64 s[10:11], exec, s[10:11]
	s_cbranch_execz .LBB0_247
	v_cmp_eq_u32_e64 s[8:9], 1, v89
	s_and_saveexec_b64 s[54:55], s[8:9]
	s_cbranch_execz .LBB0_246
	s_waitcnt vmcnt(18)
	v_pk_mul_f32 v[80:81], v[66:67], v[80:81]
	s_nop 0
	v_add_f32_e32 v80, v80, v81

.LBB0_247:
	s_andn2_saveexec_b64 s[8:9], s[10:11]
	s_cbranch_execz .LBB0_249
	s_waitcnt vmcnt(18)
	v_pk_mul_f32 v[80:81], v[66:67], v[80:81]
	s_nop 0
	v_sub_f32_e32 v80, v80, v81
.LBB0_249:
	s_or_b64 exec, exec, s[8:9]
	v_mul_f32_e32 v81, v121, v129
	v_mul_f32_e32 v124, v82, v81
	v_cmp_lt_i32_e64 s[8:9], 0, v89
	s_nop 0
	v_mov_b32_dpp v125, v124 quad_perm:[1,0,3,2] row_mask:0xf bank_mask:0xf bound_ctrl:1
	s_and_saveexec_b64 s[10:11], s[8:9]
	s_xor_b64 s[10:11], exec, s[10:11]
	s_cbranch_execz .LBB0_253
	v_cmp_eq_u32_e64 s[8:9], 1, v89
	s_and_saveexec_b64 s[54:55], s[8:9]
	s_cbranch_execz .LBB0_252
	s_waitcnt vmcnt(19)
	v_pk_mul_f32 v[124:125], v[56:57], v[124:125]
	s_nop 0
	v_add_f32_e32 v124, v124, v125

.LBB0_253:
	s_andn2_saveexec_b64 s[8:9], s[10:11]
	s_cbranch_execz .LBB0_255
	s_waitcnt vmcnt(19)
	v_pk_mul_f32 v[124:125], v[56:57], v[124:125]
	s_nop 0
	v_sub_f32_e32 v124, v124, v125
.LBB0_255:
	s_or_b64 exec, exec, s[8:9]
	v_mul_f32_e32 v81, v121, v128
	v_mul_f32_e32 v82, v83, v81
	v_cmp_lt_i32_e64 s[8:9], 0, v89
	s_nop 0
	v_mov_b32_dpp v83, v82 quad_perm:[1,0,3,2] row_mask:0xf bank_mask:0xf bound_ctrl:1
	s_and_saveexec_b64 s[10:11], s[8:9]
	s_xor_b64 s[10:11], exec, s[10:11]
	s_cbranch_execz .LBB0_259
	v_cmp_eq_u32_e64 s[8:9], 1, v89
	s_and_saveexec_b64 s[54:55], s[8:9]
	s_cbranch_execz .LBB0_258
	s_waitcnt vmcnt(19)
	v_pk_mul_f32 v[82:83], v[58:59], v[82:83]
	s_nop 0
	v_add_f32_e32 v82, v82, v83

.LBB0_259:
	s_andn2_saveexec_b64 s[8:9], s[10:11]
	s_cbranch_execz .LBB0_261
	s_waitcnt vmcnt(19)
	v_pk_mul_f32 v[82:83], v[58:59], v[82:83]
	s_nop 0
	v_sub_f32_e32 v82, v82, v83
.LBB0_261:
	s_or_b64 exec, exec, s[8:9]
	v_mul_f32_e32 v81, v121, v127
	v_mul_f32_e32 v128, v76, v81
	v_cmp_lt_i32_e64 s[8:9], 0, v89
	s_nop 0
	v_mov_b32_dpp v129, v128 quad_perm:[1,0,3,2] row_mask:0xf bank_mask:0xf bound_ctrl:1
	s_and_saveexec_b64 s[10:11], s[8:9]
	s_xor_b64 s[10:11], exec, s[10:11]
	s_cbranch_execz .LBB0_265
	v_cmp_eq_u32_e64 s[8:9], 1, v89
	s_and_saveexec_b64 s[54:55], s[8:9]
	s_cbranch_execz .LBB0_264
	s_waitcnt vmcnt(20)
	v_pk_mul_f32 v[128:129], v[52:53], v[128:129]
	s_nop 0
	v_add_f32_e32 v128, v128, v129

.LBB0_265:
	s_andn2_saveexec_b64 s[8:9], s[10:11]
	s_cbranch_execz .LBB0_267
	s_waitcnt vmcnt(20)
	v_pk_mul_f32 v[128:129], v[52:53], v[128:129]
	s_nop 0
	v_sub_f32_e32 v128, v128, v129
.LBB0_267:
	s_or_b64 exec, exec, s[8:9]
	v_mul_f32_e32 v76, v121, v126
	v_mul_f32_e32 v76, v77, v76
	v_cmp_lt_i32_e64 s[8:9], 0, v89
	s_nop 0
	v_mov_b32_dpp v77, v76 quad_perm:[1,0,3,2] row_mask:0xf bank_mask:0xf bound_ctrl:1
	s_and_saveexec_b64 s[10:11], s[8:9]
	s_xor_b64 s[10:11], exec, s[10:11]
	s_cbranch_execz .LBB0_271
	v_cmp_eq_u32_e64 s[8:9], 1, v89
	s_and_saveexec_b64 s[54:55], s[8:9]
	s_cbranch_execz .LBB0_270
	s_waitcnt vmcnt(20)
	v_pk_mul_f32 v[76:77], v[54:55], v[76:77]
	s_nop 0
	v_add_f32_e32 v76, v76, v77

.LBB0_271:
	s_andn2_saveexec_b64 s[8:9], s[10:11]
	s_cbranch_execz .LBB0_273
	s_waitcnt vmcnt(20)
	v_pk_mul_f32 v[76:77], v[54:55], v[76:77]
	s_nop 0
	v_sub_f32_e32 v76, v76, v77
.LBB0_273:
	s_or_b64 exec, exec, s[8:9]
	v_mul_f32_e32 v77, v121, v87
	v_mul_f32_e32 v126, v78, v77
	v_cmp_lt_i32_e64 s[8:9], 0, v89
	s_nop 0
	v_mov_b32_dpp v127, v126 quad_perm:[1,0,3,2] row_mask:0xf bank_mask:0xf bound_ctrl:1
	s_and_saveexec_b64 s[10:11], s[8:9]
	s_xor_b64 s[10:11], exec, s[10:11]
	s_cbranch_execz .LBB0_277
	v_cmp_eq_u32_e64 s[8:9], 1, v89
	s_and_saveexec_b64 s[54:55], s[8:9]
	s_cbranch_execz .LBB0_276
	s_waitcnt vmcnt(21)
	v_pk_mul_f32 v[126:127], v[44:45], v[126:127]
	s_nop 0
	v_add_f32_e32 v126, v126, v127

.LBB0_277:
	s_andn2_saveexec_b64 s[8:9], s[10:11]
	s_cbranch_execz .LBB0_279
	s_waitcnt vmcnt(21)
	v_pk_mul_f32 v[126:127], v[44:45], v[126:127]
	s_nop 0
	v_sub_f32_e32 v126, v126, v127
.LBB0_279:
	s_or_b64 exec, exec, s[8:9]
	v_mul_f32_e32 v77, v121, v86
	v_mul_f32_e32 v78, v79, v77
	v_cmp_lt_i32_e64 s[8:9], 0, v89
	s_nop 0
	v_mov_b32_dpp v79, v78 quad_perm:[1,0,3,2] row_mask:0xf bank_mask:0xf bound_ctrl:1
	s_and_saveexec_b64 s[10:11], s[8:9]
	s_xor_b64 s[10:11], exec, s[10:11]
	s_cbranch_execz .LBB0_283
	v_cmp_eq_u32_e64 s[8:9], 1, v89
	s_and_saveexec_b64 s[54:55], s[8:9]
	s_cbranch_execz .LBB0_282
	s_waitcnt vmcnt(21)
	v_pk_mul_f32 v[78:79], v[46:47], v[78:79]
	s_nop 0
	v_add_f32_e32 v78, v78, v79

.LBB0_283:
	s_andn2_saveexec_b64 s[8:9], s[10:11]
	s_cbranch_execz .LBB0_285
	s_waitcnt vmcnt(21)
	v_pk_mul_f32 v[78:79], v[46:47], v[78:79]
	s_nop 0
	v_sub_f32_e32 v78, v78, v79
.LBB0_285:
	s_or_b64 exec, exec, s[8:9]
	v_mul_f32_e32 v121, 0x3e38aa3b, v126
	v_mul_f32_e32 v126, 0x3e38aa3b, v76
	v_mul_f32_e32 v76, 0x3e38aa3b, v82
	v_mul_f32_e32 v77, 0x3e38aa3b, v124
	s_waitcnt vmcnt(28)
	v_lshlrev_b32_e32 v82, 16, v72
	v_and_b32_e32 v83, 0xffff0000, v72
	v_cvt_pk_bf16_f32 v85, v77, v76
	v_pk_mul_f32 v[86:87], v[82:83], v[82:83]
	v_and_b32_e32 v76, 0xffff0000, v73
	v_lshlrev_b32_e32 v77, 16, v73
	v_mul_f32_e32 v79, 0x3e38aa3b, v80
	v_mul_f32_e32 v80, 0x3e38aa3b, v84
	v_pk_mul_f32 v[72:73], v[76:77], v[76:77]
	v_add_f32_e32 v86, v86, v87
	v_mul_f32_e32 v127, 0x3e38aa3b, v128
	v_mul_f32_e32 v128, 0x3e38aa3b, v78
	v_cvt_pk_bf16_f32 v84, v80, v79
	v_and_b32_e32 v78, 0xffff0000, v74
	v_lshlrev_b32_e32 v79, 16, v74
	v_add_f32_e32 v73, v73, v86
	v_pk_mul_f32 v[124:125], v[78:79], v[78:79]
	v_add_f32_e32 v72, v72, v73
	v_and_b32_e32 v80, 0xffff0000, v75
	v_lshlrev_b32_e32 v81, 16, v75
	v_add_f32_e32 v72, v125, v72
	v_pk_mul_f32 v[74:75], v[80:81], v[80:81]
	v_add_f32_e32 v72, v124, v72
	v_add_f32_e32 v72, v75, v72
	v_add_f32_e32 v72, v74, v72
	v_cvt_pk_bf16_f32 v86, v127, v126
	v_cvt_pk_bf16_f32 v87, v121, v128
	v_add_f32_dpp v72, v72, v72 quad_perm:[1,0,3,2] row_mask:0xf bank_mask:0xf bound_ctrl:1
	global_store_dwordx4 v[122:123], v[84:87], off offset:1024
	s_nop 0
	v_add_f32_dpp v72, v72, v72 quad_perm:[2,3,0,1] row_mask:0xf bank_mask:0xf bound_ctrl:1
	s_nop 1
	v_mov_b32_dpp v73, v72 row_half_mirror row_mask:0xf bank_mask:0xf bound_ctrl:1
	s_nop 1
	v_add_f32_dpp v72, v73, v72 quad_perm:[3,2,1,0] row_mask:0xf bank_mask:0xf bound_ctrl:1
	v_fmamk_f32 v72, v72, 0x3c800000, v140
	v_mul_f32_e32 v73, 0x4b800000, v72
	v_cmp_gt_f32_e64 s[8:9], s47, v72
	s_nop 1
	v_cndmask_b32_e64 v72, v72, v73, s[8:9]
	v_rsq_f32_e32 v72, v72
	s_nop 0
	v_mul_f32_e32 v73, 0x45800000, v72
	v_cndmask_b32_e64 v84, v72, v73, s[8:9]
	v_mul_f32_e32 v72, v84, v82
	s_waitcnt vmcnt(17)
	v_mul_f32_e32 v72, v60, v72
	v_cmp_lt_i32_e64 s[8:9], 0, v89
	s_nop 0
	v_mov_b32_dpp v73, v72 quad_perm:[1,0,3,2] row_mask:0xf bank_mask:0xf bound_ctrl:1
	s_and_saveexec_b64 s[10:11], s[8:9]
	s_xor_b64 s[10:11], exec, s[10:11]
	s_cbranch_execz .LBB0_289
	v_cmp_eq_u32_e64 s[8:9], 1, v89
	s_and_saveexec_b64 s[54:55], s[8:9]
	v_pk_mul_f32 v[72:73], v[64:65], v[72:73]
	s_nop 0
	v_add_f32_e32 v72, v73, v72
	s_or_b64 exec, exec, s[54:55]

.LBB0_385:
	s_or_b64 exec, exec, s[8:9]
	s_nop 0
	v_lshlrev_b32_e32 v38, 16, v32
	v_and_b32_e32 v39, 0xffff0000, v32
	v_fma_f32 v32, |v38|, s61, 1.0
	v_rcp_f32_e32 v40, v32
	v_fma_f32 v32, |v39|, s61, 1.0
	v_rcp_f32_e32 v41, v32
	v_pk_mul_f32 v[42:43], v[38:39], v[38:39]
	v_mov_b64_e32 v[36:37], s[46:47]
	v_mul_f32_e32 v32, 0xbf38aa3b, v42
	v_exp_f32_e32 v42, v32
	v_pk_fma_f32 v[44:45], v[40:41], s[44:45], v[36:37] op_sel_hi:[1,0,0]
	v_mul_f32_e32 v32, 0xbf38aa3b, v43
	v_pk_fma_f32 v[44:45], v[40:41], v[44:45], s[48:49] op_sel_hi:[1,1,0]
	v_exp_f32_e32 v43, v32
	v_pk_fma_f32 v[44:45], v[40:41], v[44:45], s[50:51] op_sel_hi:[1,1,0]
	v_cmp_gt_f32_e64 s[8:9], 0, v39
	v_pk_fma_f32 v[44:45], v[40:41], v[44:45], s[52:53] op_sel_hi:[1,1,0]
	v_lshlrev_b32_e32 v32, 16, v33
	v_pk_mul_f32 v[40:41], v[40:41], v[44:45]
	v_and_b32_e32 v33, 0xffff0000, v33
	v_pk_mul_f32 v[40:41], v[42:43], v[40:41]
	v_mov_b32_e32 v121, v91
	v_pk_mul_f32 v[42:43], v[40:41], v[38:39]
	v_pk_fma_f32 v[40:41], v[40:41], v[38:39], v[38:39] neg_lo:[1,0,0] neg_hi:[1,0,0]
	v_fma_f32 v39, |v33|, s61, 1.0
	v_cndmask_b32_e64 v44, v41, v43, s[8:9]
	v_cmp_gt_f32_e64 s[8:9], 0, v38
	v_fma_f32 v38, |v32|, s61, 1.0
	v_rcp_f32_e32 v38, v38
	v_rcp_f32_e32 v39, v39
	v_cndmask_b32_e64 v45, v40, v42, s[8:9]
	v_pk_mul_f32 v[40:41], v[32:33], v[32:33]
	v_cmp_gt_f32_e64 s[8:9], 0, v33
	v_mul_f32_e32 v40, 0xbf38aa3b, v40
	v_pk_fma_f32 v[42:43], v[38:39], s[44:45], v[36:37] op_sel_hi:[1,0,0]
	v_mul_f32_e32 v41, 0xbf38aa3b, v41
	v_exp_f32_e32 v40, v40
	v_pk_fma_f32 v[42:43], v[38:39], v[42:43], s[48:49] op_sel_hi:[1,1,0]
	v_exp_f32_e32 v41, v41
	v_pk_fma_f32 v[42:43], v[38:39], v[42:43], s[50:51] op_sel_hi:[1,1,0]
	s_nop 0
	v_pk_fma_f32 v[42:43], v[38:39], v[42:43], s[52:53] op_sel_hi:[1,1,0]
	s_nop 0
	v_pk_mul_f32 v[38:39], v[38:39], v[42:43]
	s_nop 0
	v_pk_mul_f32 v[38:39], v[40:41], v[38:39]
	s_nop 0
	v_pk_mul_f32 v[40:41], v[38:39], v[32:33]
	v_pk_fma_f32 v[38:39], v[38:39], v[32:33], v[32:33] neg_lo:[1,0,0] neg_hi:[1,0,0]
	v_and_b32_e32 v33, 0xffff0000, v34
	v_cndmask_b32_e64 v46, v39, v41, s[8:9]
	v_cmp_gt_f32_e64 s[8:9], 0, v32
	v_lshlrev_b32_e32 v32, 16, v34
	v_fma_f32 v34, |v32|, s61, 1.0
	v_cndmask_b32_e64 v47, v38, v40, s[8:9]
	v_rcp_f32_e32 v38, v34
	v_fma_f32 v34, |v33|, s61, 1.0
	v_rcp_f32_e32 v39, v34
	v_pk_mul_f32 v[40:41], v[32:33], v[32:33]
	v_cmp_gt_f32_e64 s[8:9], 0, v33
	v_mul_f32_e32 v34, 0xbf38aa3b, v40
	v_exp_f32_e32 v40, v34
	v_pk_fma_f32 v[42:43], v[38:39], s[44:45], v[36:37] op_sel_hi:[1,0,0]
	v_mul_f32_e32 v34, 0xbf38aa3b, v41
	v_pk_fma_f32 v[42:43], v[38:39], v[42:43], s[48:49] op_sel_hi:[1,1,0]
	v_exp_f32_e32 v41, v34
	v_pk_fma_f32 v[42:43], v[38:39], v[42:43], s[50:51] op_sel_hi:[1,1,0]
	s_nop 0
	v_pk_fma_f32 v[42:43], v[38:39], v[42:43], s[52:53] op_sel_hi:[1,1,0]
	s_nop 0
	v_pk_mul_f32 v[38:39], v[38:39], v[42:43]
	s_nop 0
	v_pk_mul_f32 v[38:39], v[40:41], v[38:39]
	s_nop 0
	v_pk_mul_f32 v[40:41], v[38:39], v[32:33]
	v_pk_fma_f32 v[38:39], v[38:39], v[32:33], v[32:33] neg_lo:[1,0,0] neg_hi:[1,0,0]
	v_and_b32_e32 v33, 0xffff0000, v35
	v_cndmask_b32_e64 v42, v39, v41, s[8:9]
	v_cmp_gt_f32_e64 s[8:9], 0, v32
	v_lshlrev_b32_e32 v32, 16, v35
	v_fma_f32 v34, |v32|, s61, 1.0
	v_fma_f32 v35, |v33|, s61, 1.0
	v_rcp_f32_e32 v34, v34
	v_rcp_f32_e32 v35, v35
	v_cndmask_b32_e64 v43, v38, v40, s[8:9]
	v_pk_mul_f32 v[38:39], v[32:33], v[32:33]
	v_cmp_gt_f32_e64 s[8:9], 0, v33
	v_mul_f32_e32 v38, 0xbf38aa3b, v38
	v_pk_fma_f32 v[40:41], v[34:35], s[44:45], v[36:37] op_sel_hi:[1,0,0]
	v_mul_f32_e32 v39, 0xbf38aa3b, v39
	v_exp_f32_e32 v38, v38
	v_pk_fma_f32 v[40:41], v[34:35], v[40:41], s[48:49] op_sel_hi:[1,1,0]
	v_exp_f32_e32 v39, v39
	v_pk_fma_f32 v[40:41], v[34:35], v[40:41], s[50:51] op_sel_hi:[1,1,0]
	s_nop 0
	v_pk_fma_f32 v[40:41], v[34:35], v[40:41], s[52:53] op_sel_hi:[1,1,0]
	s_nop 0
	v_pk_mul_f32 v[34:35], v[34:35], v[40:41]
	v_cvt_pk_bf16_f32 v40, v43, v42
	v_pk_mul_f32 v[34:35], v[38:39], v[34:35]
	s_nop 0
	v_pk_mul_f32 v[38:39], v[34:35], v[32:33]
	v_pk_fma_f32 v[34:35], v[34:35], v[32:33], v[32:33] neg_lo:[1,0,0] neg_hi:[1,0,0]
	s_nop 0
	v_cndmask_b32_e64 v33, v35, v39, s[8:9]
	v_cmp_gt_f32_e64 s[8:9], 0, v32
	v_and_b32_e32 v35, 0xffff0000, v30
	v_cvt_pk_bf16_f32 v39, v47, v46
	v_cndmask_b32_e64 v32, v34, v38, s[8:9]
	v_lshlrev_b32_e32 v34, 16, v30
	v_fma_f32 v30, |v34|, s61, 1.0
	v_rcp_f32_e32 v42, v30
	v_fma_f32 v30, |v35|, s61, 1.0
	v_rcp_f32_e32 v43, v30
	v_cvt_pk_bf16_f32 v38, v45, v44
	v_pk_mul_f32 v[44:45], v[34:35], v[34:35]
	v_cmp_gt_f32_e64 s[8:9], 0, v35
	v_mul_f32_e32 v30, 0xbf38aa3b, v44
	v_exp_f32_e32 v44, v30
	v_pk_fma_f32 v[46:47], v[42:43], s[44:45], v[36:37] op_sel_hi:[1,0,0]
	v_mul_f32_e32 v30, 0xbf38aa3b, v45
	v_pk_fma_f32 v[46:47], v[42:43], v[46:47], s[48:49] op_sel_hi:[1,1,0]
	v_exp_f32_e32 v45, v30
	v_pk_fma_f32 v[46:47], v[42:43], v[46:47], s[50:51] op_sel_hi:[1,1,0]
	v_lshlrev_b32_e32 v30, 16, v31
	v_pk_fma_f32 v[46:47], v[42:43], v[46:47], s[52:53] op_sel_hi:[1,1,0]
	v_and_b32_e32 v31, 0xffff0000, v31
	v_pk_mul_f32 v[42:43], v[42:43], v[46:47]
	v_cvt_pk_bf16_f32 v41, v32, v33
	v_pk_mul_f32 v[42:43], v[44:45], v[42:43]
	v_lshl_add_u64 v[32:33], v[118:119], 0, v[120:121]
	v_pk_mul_f32 v[44:45], v[42:43], v[34:35]
	v_pk_fma_f32 v[42:43], v[42:43], v[34:35], v[34:35] neg_lo:[1,0,0] neg_hi:[1,0,0]
	s_nop 0
	v_cndmask_b32_e64 v35, v43, v45, s[8:9]
	v_cmp_gt_f32_e64 s[8:9], 0, v34
	v_fma_f32 v43, |v31|, s61, 1.0
	v_rcp_f32_e32 v43, v43
	v_cndmask_b32_e64 v34, v42, v44, s[8:9]
	v_fma_f32 v42, |v30|, s61, 1.0
	v_rcp_f32_e32 v42, v42
	v_pk_mul_f32 v[44:45], v[30:31], v[30:31]
	v_cmp_gt_f32_e64 s[8:9], 0, v31
	v_mul_f32_e32 v44, 0xbf38aa3b, v44
	v_pk_fma_f32 v[46:47], v[42:43], s[44:45], v[36:37] op_sel_hi:[1,0,0]
	v_mul_f32_e32 v45, 0xbf38aa3b, v45
	v_exp_f32_e32 v44, v44
	v_pk_fma_f32 v[46:47], v[42:43], v[46:47], s[48:49] op_sel_hi:[1,1,0]
	v_exp_f32_e32 v45, v45
	v_pk_fma_f32 v[46:47], v[42:43], v[46:47], s[50:51] op_sel_hi:[1,1,0]
	s_nop 0
	v_pk_fma_f32 v[46:47], v[42:43], v[46:47], s[52:53] op_sel_hi:[1,1,0]
	s_nop 0
	v_pk_mul_f32 v[42:43], v[42:43], v[46:47]
	s_nop 0
	v_pk_mul_f32 v[42:43], v[44:45], v[42:43]
	s_nop 0
	v_pk_mul_f32 v[44:45], v[42:43], v[30:31]
	v_pk_fma_f32 v[42:43], v[42:43], v[30:31], v[30:31] neg_lo:[1,0,0] neg_hi:[1,0,0]
	s_nop 0
	v_cndmask_b32_e64 v31, v43, v45, s[8:9]
	v_cmp_gt_f32_e64 s[8:9], 0, v30
	v_and_b32_e32 v43, 0xffff0000, v28
	s_nop 0
	v_cndmask_b32_e64 v30, v42, v44, s[8:9]
	v_lshlrev_b32_e32 v42, 16, v28
	v_fma_f32 v28, |v42|, s61, 1.0
	v_rcp_f32_e32 v44, v28
	v_fma_f32 v28, |v43|, s61, 1.0
	v_rcp_f32_e32 v45, v28
	v_pk_mul_f32 v[46:47], v[42:43], v[42:43]
	v_cmp_gt_f32_e64 s[8:9], 0, v43
	v_mul_f32_e32 v28, 0xbf38aa3b, v46
	v_exp_f32_e32 v46, v28
	v_pk_fma_f32 v[48:49], v[44:45], s[44:45], v[36:37] op_sel_hi:[1,0,0]
	v_mul_f32_e32 v28, 0xbf38aa3b, v47
	v_pk_fma_f32 v[48:49], v[44:45], v[48:49], s[48:49] op_sel_hi:[1,1,0]
	v_exp_f32_e32 v47, v28
	v_pk_fma_f32 v[48:49], v[44:45], v[48:49], s[50:51] op_sel_hi:[1,1,0]
	s_nop 0
	v_pk_fma_f32 v[48:49], v[44:45], v[48:49], s[52:53] op_sel_hi:[1,1,0]
	s_nop 0
	v_pk_mul_f32 v[44:45], v[44:45], v[48:49]
	s_nop 0
	v_pk_mul_f32 v[44:45], v[46:47], v[44:45]
	s_nop 0
	v_pk_mul_f32 v[46:47], v[44:45], v[42:43]
	v_pk_fma_f32 v[44:45], v[44:45], v[42:43], v[42:43] neg_lo:[1,0,0] neg_hi:[1,0,0]
	s_nop 0
	v_cndmask_b32_e64 v43, v45, v47, s[8:9]
	v_cmp_gt_f32_e64 s[8:9], 0, v42
	s_nop 1
	v_cndmask_b32_e64 v42, v44, v46, s[8:9]
	v_add_f32_e32 v28, 0, v42
	v_add_f32_e32 v48, v43, v28
	v_lshlrev_b32_e32 v28, 16, v29
	v_and_b32_e32 v29, 0xffff0000, v29
	v_fma_f32 v44, |v28|, s61, 1.0
	v_fma_f32 v45, |v29|, s61, 1.0
	v_rcp_f32_e32 v44, v44
	v_rcp_f32_e32 v45, v45
	v_pk_mul_f32 v[46:47], v[28:29], v[28:29]
	v_cmp_gt_f32_e64 s[8:9], 0, v29
	v_mul_f32_e32 v46, 0xbf38aa3b, v46
	v_pk_fma_f32 v[36:37], v[44:45], s[44:45], v[36:37] op_sel_hi:[1,0,0]
	v_mul_f32_e32 v47, 0xbf38aa3b, v47
	v_exp_f32_e32 v46, v46
	v_pk_fma_f32 v[36:37], v[44:45], v[36:37], s[48:49] op_sel_hi:[1,1,0]
	v_exp_f32_e32 v47, v47
	v_pk_fma_f32 v[36:37], v[44:45], v[36:37], s[50:51] op_sel_hi:[1,1,0]
	s_nop 0
	v_pk_fma_f32 v[36:37], v[44:45], v[36:37], s[52:53] op_sel_hi:[1,1,0]
	s_nop 0
	v_pk_mul_f32 v[36:37], v[44:45], v[36:37]
	s_nop 0
	v_pk_mul_f32 v[36:37], v[46:47], v[36:37]
	s_nop 0
	v_pk_mul_f32 v[44:45], v[36:37], v[28:29]
	v_pk_fma_f32 v[36:37], v[36:37], v[28:29], v[28:29] neg_lo:[1,0,0] neg_hi:[1,0,0]
	s_nop 0
	v_cndmask_b32_e64 v29, v37, v45, s[8:9]
	v_cmp_gt_f32_e64 s[8:9], 0, v28
	s_nop 1
	v_cndmask_b32_e64 v28, v36, v44, s[8:9]
	v_add_f32_e32 v36, v28, v48
	v_add_f32_e32 v36, v29, v36
	v_add_f32_e32 v36, v34, v36
	v_add_f32_e32 v36, v35, v36
	v_add_f32_e32 v36, v30, v36
	v_add_f32_e32 v36, v31, v36
	v_mov_b32_e32 v37, v36
	v_mov_b32_e32 v44, v36
	s_nop 1
	v_permlane32_swap_b32_e32 v37, v44
	v_cndmask_b32_e64 v37, v37, v44, s[6:7]
	v_add_f32_e32 v36, v36, v37
	v_mov_b32_e32 v37, v36
	v_mov_b32_e32 v44, v36
	s_nop 1
	v_permlane16_swap_b32_e32 v37, v44
	v_cndmask_b32_e64 v37, v37, v44, s[4:5]
	v_add_f32_e32 v36, v36, v37
	s_nop 1
	v_add_f32_dpp v36, v36, v36 row_ror:8 row_mask:0xf bank_mask:0xf bound_ctrl:1
	s_nop 1
	v_mov_b32_dpp v37, v36 row_half_mirror row_mask:0xf bank_mask:0xf bound_ctrl:1
	s_nop 1
	v_add_f32_dpp v36, v37, v36 quad_perm:[3,2,1,0] row_mask:0xf bank_mask:0xf bound_ctrl:1
	s_nop 1
	v_add_f32_dpp v36, v36, v36 quad_perm:[2,3,0,1] row_mask:0xf bank_mask:0xf bound_ctrl:1
	s_nop 1
	v_add_f32_dpp v36, v36, v36 quad_perm:[1,0,3,2] row_mask:0xf bank_mask:0xf bound_ctrl:1
	v_mul_f32_e32 v36, 0x3b000000, v36
	v_pk_add_f32 v[42:43], v[42:43], v[36:37] op_sel_hi:[1,0] neg_lo:[0,1] neg_hi:[0,1]
	v_pk_add_f32 v[28:29], v[28:29], v[36:37] op_sel_hi:[1,0] neg_lo:[0,1] neg_hi:[0,1]
	v_pk_mul_f32 v[44:45], v[42:43], v[42:43]
	v_pk_mul_f32 v[46:47], v[28:29], v[28:29]
	v_add_f32_e32 v44, v44, v45
	v_pk_add_f32 v[34:35], v[34:35], v[36:37] op_sel_hi:[1,0] neg_lo:[0,1] neg_hi:[0,1]
	v_add_f32_e32 v44, v46, v44
	v_pk_mul_f32 v[48:49], v[34:35], v[34:35]
	v_add_f32_e32 v44, v47, v44
	v_pk_add_f32 v[30:31], v[30:31], v[36:37] op_sel_hi:[1,0] neg_lo:[0,1] neg_hi:[0,1]
	v_add_f32_e32 v44, v48, v44
	v_pk_mul_f32 v[36:37], v[30:31], v[30:31]
	v_add_f32_e32 v44, v49, v44
	v_add_f32_e32 v36, v36, v44
	v_add_f32_e32 v36, v37, v36
	v_mov_b32_e32 v37, v36
	v_mov_b32_e32 v44, v36
	s_nop 1
	v_permlane32_swap_b32_e32 v37, v44
	v_cndmask_b32_e64 v37, v37, v44, s[6:7]
	v_add_f32_e32 v36, v36, v37
	v_mov_b32_e32 v37, v36
	v_mov_b32_e32 v44, v36
	s_nop 1
	v_permlane16_swap_b32_e32 v37, v44
	v_cndmask_b32_e64 v37, v37, v44, s[4:5]
	v_add_f32_e32 v36, v36, v37
	s_nop 1
	v_add_f32_dpp v36, v36, v36 row_ror:8 row_mask:0xf bank_mask:0xf bound_ctrl:1
	s_nop 1
	v_mov_b32_dpp v37, v36 row_half_mirror row_mask:0xf bank_mask:0xf bound_ctrl:1
	s_nop 1
	v_add_f32_dpp v36, v37, v36 quad_perm:[3,2,1,0] row_mask:0xf bank_mask:0xf bound_ctrl:1
	s_nop 1
	v_add_f32_dpp v36, v36, v36 quad_perm:[2,3,0,1] row_mask:0xf bank_mask:0xf bound_ctrl:1
	s_nop 1
	v_add_f32_dpp v36, v36, v36 quad_perm:[1,0,3,2] row_mask:0xf bank_mask:0xf bound_ctrl:1
	v_fmamk_f32 v36, v36, 0x3b000000, v140
	v_mul_f32_e32 v37, 0x4b800000, v36
	v_cmp_gt_f32_e64 s[8:9], s47, v36
	s_nop 1
	v_cndmask_b32_e64 v36, v36, v37, s[8:9]
	v_rsq_f32_e32 v44, v36
	v_add_co_u32_e64 v36, s[10:11], s53, v32
	s_nop 1
	v_addc_co_u32_e64 v37, s[10:11], 0, v33, s[10:11]
	global_store_dwordx4 v[36:37], v[38:41], off offset:2048
	s_nop 1
	v_mul_f32_e32 v38, 0x45800000, v44
	v_cndmask_b32_e64 v38, v44, v38, s[8:9]
	v_pk_mul_f32 v[40:41], v[42:43], v[38:39] op_sel_hi:[1,0]
	s_waitcnt vmcnt(24)
	v_pk_fma_f32 v[20:21], v[20:21], v[40:41], v[24:25]
	v_pk_mul_f32 v[24:25], v[34:35], v[38:39] op_sel_hi:[1,0]
	s_nop 0
	v_pk_fma_f32 v[12:13], v[12:13], v[24:25], v[16:17]
	v_pk_mul_f32 v[16:17], v[28:29], v[38:39] op_sel_hi:[1,0]
	s_nop 0
	v_pk_fma_f32 v[22:23], v[22:23], v[16:17], v[26:27]
	v_pk_mul_f32 v[16:17], v[30:31], v[38:39] op_sel_hi:[1,0]
	s_nop 0
	v_pk_fma_f32 v[14:15], v[14:15], v[16:17], v[18:19]
	v_cvt_pk_bf16_f32 v16, v20, v21
	v_cvt_pk_bf16_f32 v17, v22, v23
	v_cvt_pk_bf16_f32 v18, v12, v13
	v_cvt_pk_bf16_f32 v19, v14, v15
	global_store_dwordx4 v[36:37], v[16:19], off offset:3072
	s_and_saveexec_b64 s[8:9], vcc
	s_cbranch_execz .LBB0_184
	v_lshlrev_b64 v[16:17], 11, v[80:81]
	v_lshl_add_u64 v[16:17], v[100:101], 0, v[16:17]
	global_store_dwordx4 v[16:17], v[20:23], off
	global_store_dwordx4 v[16:17], v[12:15], off offset:16
	s_branch .LBB0_184
